# P3 per-row ops: hand-scheduled fast path (all 32 row loads issued together) for rows >= 2048
# speedup vs baseline: 1.0690x; 1.0078x over previous
.LBB0_278:
	s_andn2_saveexec_b64 s[36:37], s[36:37]
	s_or_b64 exec, exec, s[36:37]
	v_min_i32_e32 v9, 15, v60
	v_add_u32_e32 v9, 1, v9
	v_cvt_f32_i32_e32 v9, v9
	v_readlane_b32 s4, v250, 27
	v_lshl_add_u64 v[10:11], v[10:11], 0, s[86:87]
	v_lshl_add_u64 v[12:13], v[12:13], 0, s[86:87]
	v_div_scale_f32 v20, s[36:37], v9, v9, 1.0
	v_rcp_f32_e32 v21, v20
	s_waitcnt vmcnt(11)
	v_div_scale_f32 v30, vcc, 1.0, v9, 1.0
	v_add_u32_e32 v8, s4, v8
	v_fma_f32 v31, -v20, v21, 1.0
	v_fmac_f32_e32 v21, v31, v21
	v_mul_f32_e32 v31, v30, v21
	s_waitcnt vmcnt(10)
	v_fma_f32 v32, -v20, v31, v30
	v_fmac_f32_e32 v31, v32, v21
	v_fma_f32 v20, -v20, v31, v30
	v_div_fmas_f32 v20, v20, v21, v31
	v_div_fixup_f32 v20, v20, v9, 1.0
	v_pk_fma_f32 v[24:25], v[20:21], v[28:29], v[24:25] op_sel_hi:[0,1,1] neg_lo:[0,0,1] neg_hi:[0,0,1]
	v_pk_fma_f32 v[20:21], v[20:21], v[26:27], v[22:23] op_sel_hi:[0,1,1] neg_lo:[0,0,1] neg_hi:[0,0,1]
	v_add_u32_e32 v9, 15, v8
	v_pk_mov_b32 v[20:21], v[20:21], v[20:21] op_sel:[1,0]
	v_cmp_lt_i32_e32 vcc, s77, v9
	v_cvt_pk_bf16_f32 v22, v24, v25
	v_cvt_pk_bf16_f32 v23, v20, v21
	v_lshl_add_u64 v[14:15], v[14:15], 0, s[8:9]
	s_or_b64 s[84:85], vcc, s[84:85]
	v_lshl_add_u64 v[16:17], v[16:17], 0, s[10:11]
	global_store_dwordx2 v[18:19], v[22:23], off offset:512
	v_readlane_b32 s5, v250, 28
	s_branch .Lp3fast

.Lp3fast:
	s_mov_b64 s[36:37], s[0:1]
	s_add_u32 s38, s14, 0xe700000
	s_addc_u32 s39, s15, 0
	s_add_u32 s40, s14, 0xeb20000
	s_addc_u32 s41, s15, 0
	s_add_u32 s42, s14, 0xec28000
	s_addc_u32 s43, s15, 0
	v_readlane_b32 s45, v250, 27
	v_readfirstlane_b32 s44, v8
	v_lshlrev_b32_e32 v64, 3, v180
	v_lshlrev_b32_e32 v65, 1, v180
	v_lshrrev_b32_e32 v67, 4, v180
	v_lshlrev_b32_e32 v67, 10, v67
	v_bfe_u32 v68, v180, 3, 1
	v_lshl_add_u32 v67, v68, 9, v67
	v_and_b32_e32 v68, 7, v180
	v_lshl_add_u32 v67, v68, 1, v67
	global_load_dwordx4 v[72:75], v[0:1], off
	global_load_dword v76, v[2:3], off
	v_mov_b32_e32 v184, 0.5
	v_mov_b32_e32 v186, 0x3e800000
	v_mov_b32_e32 v188, 0x3e000000
	v_mov_b32_e32 v190, 0x3d800000
	s_add_u32 s44, s44, 15
.Lp3f_loop:
	s_mov_b32 s48, s44
	s_mov_b32 s49, 0
	s_lshl_b64 s[48:49], s[48:49], 14
	s_add_u32 s48, s48, s36
	s_addc_u32 s49, s49, s37
	s_add_u32 s100, s48, 0x1000
	s_addc_u32 s101, s49, 0
	global_load_dwordx2 v[80:81], v64, s[100:101]
	global_load_ushort v82, v65, s[100:101] offset:1536
	s_mov_b64 s[46:47], s[100:101]
	global_load_dwordx2 v[84:85], v64, s[46:47] offset:1680
	global_load_dwordx2 v[86:87], v64, s[46:47] offset:2192
	global_load_dwordx2 v[88:89], v64, s[46:47] offset:2704
	global_load_dwordx2 v[90:91], v64, s[46:47] offset:3216
	s_sub_u32 s46, s46, 0x4000
	s_subb_u32 s47, s47, 0
	global_load_dwordx2 v[92:93], v64, s[46:47] offset:1680
	global_load_dwordx2 v[94:95], v64, s[46:47] offset:2192
	global_load_dwordx2 v[96:97], v64, s[46:47] offset:2704
	global_load_dwordx2 v[98:99], v64, s[46:47] offset:3216
	s_sub_u32 s46, s46, 0x4000
	s_subb_u32 s47, s47, 0
	global_load_dwordx2 v[100:101], v64, s[46:47] offset:2192
	global_load_dwordx2 v[102:103], v64, s[46:47] offset:2704
	global_load_dwordx2 v[104:105], v64, s[46:47] offset:3216
	s_sub_u32 s46, s46, 0x4000
	s_subb_u32 s47, s47, 0
	global_load_dwordx2 v[106:107], v64, s[46:47] offset:2192
	global_load_dwordx2 v[108:109], v64, s[46:47] offset:2704
	global_load_dwordx2 v[110:111], v64, s[46:47] offset:3216
	s_sub_u32 s46, s46, 0x4000
	s_subb_u32 s47, s47, 0
	global_load_dwordx2 v[112:113], v64, s[46:47] offset:2704
	global_load_dwordx2 v[114:115], v64, s[46:47] offset:3216
	s_sub_u32 s46, s46, 0x4000
	s_subb_u32 s47, s47, 0
	global_load_dwordx2 v[116:117], v64, s[46:47] offset:2704
	global_load_dwordx2 v[118:119], v64, s[46:47] offset:3216
	s_sub_u32 s46, s46, 0x4000
	s_subb_u32 s47, s47, 0
	global_load_dwordx2 v[120:121], v64, s[46:47] offset:2704
	global_load_dwordx2 v[122:123], v64, s[46:47] offset:3216
	s_sub_u32 s46, s46, 0x4000
	s_subb_u32 s47, s47, 0
	global_load_dwordx2 v[124:125], v64, s[46:47] offset:2704
	global_load_dwordx2 v[126:127], v64, s[46:47] offset:3216
	s_sub_u32 s46, s46, 0x4000
	s_subb_u32 s47, s47, 0
	global_load_dwordx2 v[128:129], v64, s[46:47] offset:3216
	s_sub_u32 s46, s46, 0x4000
	s_subb_u32 s47, s47, 0
	global_load_dwordx2 v[130:131], v64, s[46:47] offset:3216
	s_sub_u32 s46, s46, 0x4000
	s_subb_u32 s47, s47, 0
	global_load_dwordx2 v[132:133], v64, s[46:47] offset:3216
	s_sub_u32 s46, s46, 0x4000
	s_subb_u32 s47, s47, 0
	global_load_dwordx2 v[134:135], v64, s[46:47] offset:3216
	s_sub_u32 s46, s46, 0x4000
	s_subb_u32 s47, s47, 0
	global_load_dwordx2 v[136:137], v64, s[46:47] offset:3216
	s_sub_u32 s46, s46, 0x4000
	s_subb_u32 s47, s47, 0
	global_load_dwordx2 v[138:139], v64, s[46:47] offset:3216
	s_sub_u32 s46, s46, 0x4000
	s_subb_u32 s47, s47, 0
	global_load_dwordx2 v[140:141], v64, s[46:47] offset:3216
	s_sub_u32 s46, s46, 0x4000
	s_subb_u32 s47, s47, 0
	global_load_dwordx2 v[142:143], v64, s[46:47] offset:3216
	s_lshl_b32 s46, s44, 9
	s_add_u32 s98, s38, s46
	s_addc_u32 s99, s39, 0
	s_lshr_b32 s46, s44, 5
	s_lshl_b32 s46, s46, 12
	s_and_b32 s47, s44, 31
	s_lshl_b32 s47, s47, 4
	s_add_u32 s46, s46, s47
	s_add_u32 s100, s40, s46
	s_addc_u32 s101, s41, 0
	s_lshl_b32 s46, s44, 11
	s_add_u32 s48, s42, s46
	s_addc_u32 s49, s43, 0
	s_mov_b32 s46, 0x800000
	s_movk_i32 s47, 0x7fff
	s_waitcnt vmcnt(31)
	v_lshlrev_b32_e32 v144, 16, v80
	v_and_b32_e32 v145, 0xffff0000, v80
	v_lshlrev_b32_e32 v146, 16, v81
	v_and_b32_e32 v147, 0xffff0000, v81
	v_pk_mul_f32 v[148:149], v[144:145], v[144:145]
	v_pk_mul_f32 v[150:151], v[146:147], v[146:147]
	v_add_f32_e32 v152, v148, v149
	v_add_f32_e32 v152, v152, v150
	v_add_f32_e32 v152, v151, v152
	ds_bpermute_b32 v153, v5, v152
	s_waitcnt lgkmcnt(0)
	v_add_f32_e32 v152, v152, v153
	ds_bpermute_b32 v153, v54, v152
	s_waitcnt lgkmcnt(0)
	v_add_f32_e32 v152, v152, v153
	ds_bpermute_b32 v153, v55, v152
	s_waitcnt lgkmcnt(0)
	v_add_f32_e32 v152, v152, v153
	ds_bpermute_b32 v153, v56, v152
	s_waitcnt lgkmcnt(0)
	v_add_f32_e32 v152, v152, v153
	ds_bpermute_b32 v153, v57, v152
	s_waitcnt lgkmcnt(0)
	v_add_f32_e32 v152, v152, v153
	ds_bpermute_b32 v153, v58, v152
	s_waitcnt lgkmcnt(0)
	v_add_f32_e32 v152, v152, v153
	v_fmamk_f32 v152, v152, 0x3b800000, v170
	v_cmp_gt_f32_e32 vcc, s46, v152
	v_mul_f32_e32 v153, 0x4b800000, v152
	s_nop 0
	v_cndmask_b32_e32 v152, v152, v153, vcc
	v_rsq_f32_e32 v152, v152
	s_nop 0
	v_mul_f32_e32 v153, 0x45800000, v152
	v_cndmask_b32_e32 v154, v152, v153, vcc
	v_pk_mul_f32 v[144:145], v[154:155], v[144:145] op_sel_hi:[0,1]
	v_pk_mul_f32 v[144:145], v[72:73], v[144:145]
	v_pk_mul_f32 v[146:147], v[154:155], v[146:147] op_sel_hi:[0,1]
	v_pk_mul_f32 v[146:147], v[74:75], v[146:147]
	v_cvt_pk_bf16_f32 v144, v144, v145
	v_cvt_pk_bf16_f32 v145, v146, v147
	global_store_dwordx2 v64, v[144:145], s[98:99]
	s_waitcnt vmcnt(31)
	v_lshlrev_b32_e32 v156, 16, v82
	v_mul_f32_e32 v157, v156, v156
	ds_bpermute_b32 v157, v5, v157
	s_waitcnt lgkmcnt(0)
	v_fmac_f32_e32 v157, v156, v156
	ds_bpermute_b32 v158, v54, v157
	s_waitcnt lgkmcnt(0)
	v_add_f32_e32 v157, v157, v158
	ds_bpermute_b32 v158, v55, v157
	s_waitcnt lgkmcnt(0)
	v_add_f32_e32 v157, v157, v158
	ds_bpermute_b32 v158, v56, v157
	s_waitcnt lgkmcnt(0)
	v_add_f32_e32 v157, v157, v158
	ds_bpermute_b32 v158, v57, v157
	s_waitcnt lgkmcnt(0)
	v_add_f32_e32 v157, v157, v158
	ds_bpermute_b32 v158, v58, v157
	s_waitcnt lgkmcnt(0)
	v_add_f32_e32 v157, v157, v158
	v_fmamk_f32 v157, v157, 0x3c800000, v170
	v_cmp_gt_f32_e32 vcc, s46, v157
	v_mul_f32_e32 v158, 0x4b800000, v157
	s_nop 0
	v_cndmask_b32_e32 v157, v157, v158, vcc
	v_rsq_f32_e32 v157, v157
	s_nop 0
	v_mul_f32_e32 v158, 0x45800000, v157
	v_cndmask_b32_e32 v157, v157, v158, vcc
	v_mul_f32_e32 v156, v157, v156
	v_mul_f32_e32 v156, v76, v156
	v_bfe_u32 v158, v156, 16, 1
	v_add3_u32 v156, v156, v158, s47
	global_store_short_d16_hi v67, v156, s[100:101]
	s_waitcnt vmcnt(2)
	v_lshlrev_b32_e32 v160, 16, v92
	v_and_b32_e32 v161, 0xffff0000, v92
	v_lshlrev_b32_e32 v162, 16, v93
	v_and_b32_e32 v163, 0xffff0000, v93
	v_pk_add_f32 v[160:161], v[160:161], 0 op_sel_hi:[1,0]
	v_pk_add_f32 v[162:163], v[162:163], 0 op_sel_hi:[1,0]
	v_lshlrev_b32_e32 v164, 16, v84
	v_and_b32_e32 v165, 0xffff0000, v84
	v_lshlrev_b32_e32 v166, 16, v85
	v_and_b32_e32 v167, 0xffff0000, v85
	v_pk_add_f32 v[160:161], v[160:161], v[164:165]
	v_pk_add_f32 v[162:163], v[162:163], v[166:167]
	v_pk_fma_f32 v[160:161], v[184:185], v[160:161], v[164:165] op_sel_hi:[0,1,1] neg_lo:[0,0,1] neg_hi:[0,0,1]
	v_pk_fma_f32 v[162:163], v[184:185], v[162:163], v[166:167] op_sel_hi:[0,1,1] neg_lo:[0,0,1] neg_hi:[0,0,1]
	v_cvt_pk_bf16_f32 v160, v160, v161
	v_cvt_pk_bf16_f32 v161, v162, v163
	global_store_dwordx2 v64, v[160:161], s[48:49]
	s_nop 1
	v_lshlrev_b32_e32 v160, 16, v106
	v_and_b32_e32 v161, 0xffff0000, v106
	v_lshlrev_b32_e32 v162, 16, v107
	v_and_b32_e32 v163, 0xffff0000, v107
	v_pk_add_f32 v[160:161], v[160:161], 0 op_sel_hi:[1,0]
	v_pk_add_f32 v[162:163], v[162:163], 0 op_sel_hi:[1,0]
	v_lshlrev_b32_e32 v164, 16, v100
	v_and_b32_e32 v165, 0xffff0000, v100
	v_lshlrev_b32_e32 v166, 16, v101
	v_and_b32_e32 v167, 0xffff0000, v101
	v_pk_add_f32 v[160:161], v[160:161], v[164:165]
	v_pk_add_f32 v[162:163], v[162:163], v[166:167]
	v_lshlrev_b32_e32 v164, 16, v94
	v_and_b32_e32 v165, 0xffff0000, v94
	v_lshlrev_b32_e32 v166, 16, v95
	v_and_b32_e32 v167, 0xffff0000, v95
	v_pk_add_f32 v[160:161], v[160:161], v[164:165]
	v_pk_add_f32 v[162:163], v[162:163], v[166:167]
	v_lshlrev_b32_e32 v164, 16, v86
	v_and_b32_e32 v165, 0xffff0000, v86
	v_lshlrev_b32_e32 v166, 16, v87
	v_and_b32_e32 v167, 0xffff0000, v87
	v_pk_add_f32 v[160:161], v[160:161], v[164:165]
	v_pk_add_f32 v[162:163], v[162:163], v[166:167]
	v_pk_fma_f32 v[160:161], v[186:187], v[160:161], v[164:165] op_sel_hi:[0,1,1] neg_lo:[0,0,1] neg_hi:[0,0,1]
	v_pk_fma_f32 v[162:163], v[186:187], v[162:163], v[166:167] op_sel_hi:[0,1,1] neg_lo:[0,0,1] neg_hi:[0,0,1]
	v_cvt_pk_bf16_f32 v160, v160, v161
	v_cvt_pk_bf16_f32 v161, v162, v163
	global_store_dwordx2 v64, v[160:161], s[48:49] offset:512
	s_nop 1
	v_lshlrev_b32_e32 v160, 16, v124
	v_and_b32_e32 v161, 0xffff0000, v124
	v_lshlrev_b32_e32 v162, 16, v125
	v_and_b32_e32 v163, 0xffff0000, v125
	v_pk_add_f32 v[160:161], v[160:161], 0 op_sel_hi:[1,0]
	v_pk_add_f32 v[162:163], v[162:163], 0 op_sel_hi:[1,0]
	v_lshlrev_b32_e32 v164, 16, v120
	v_and_b32_e32 v165, 0xffff0000, v120
	v_lshlrev_b32_e32 v166, 16, v121
	v_and_b32_e32 v167, 0xffff0000, v121
	v_pk_add_f32 v[160:161], v[160:161], v[164:165]
	v_pk_add_f32 v[162:163], v[162:163], v[166:167]
	v_lshlrev_b32_e32 v164, 16, v116
	v_and_b32_e32 v165, 0xffff0000, v116
	v_lshlrev_b32_e32 v166, 16, v117
	v_and_b32_e32 v167, 0xffff0000, v117
	v_pk_add_f32 v[160:161], v[160:161], v[164:165]
	v_pk_add_f32 v[162:163], v[162:163], v[166:167]
	v_lshlrev_b32_e32 v164, 16, v112
	v_and_b32_e32 v165, 0xffff0000, v112
	v_lshlrev_b32_e32 v166, 16, v113
	v_and_b32_e32 v167, 0xffff0000, v113
	v_pk_add_f32 v[160:161], v[160:161], v[164:165]
	v_pk_add_f32 v[162:163], v[162:163], v[166:167]
	v_lshlrev_b32_e32 v164, 16, v108
	v_and_b32_e32 v165, 0xffff0000, v108
	v_lshlrev_b32_e32 v166, 16, v109
	v_and_b32_e32 v167, 0xffff0000, v109
	v_pk_add_f32 v[160:161], v[160:161], v[164:165]
	v_pk_add_f32 v[162:163], v[162:163], v[166:167]
	v_lshlrev_b32_e32 v164, 16, v102
	v_and_b32_e32 v165, 0xffff0000, v102
	v_lshlrev_b32_e32 v166, 16, v103
	v_and_b32_e32 v167, 0xffff0000, v103
	v_pk_add_f32 v[160:161], v[160:161], v[164:165]
	v_pk_add_f32 v[162:163], v[162:163], v[166:167]
	v_lshlrev_b32_e32 v164, 16, v96
	v_and_b32_e32 v165, 0xffff0000, v96
	v_lshlrev_b32_e32 v166, 16, v97
	v_and_b32_e32 v167, 0xffff0000, v97
	v_pk_add_f32 v[160:161], v[160:161], v[164:165]
	v_pk_add_f32 v[162:163], v[162:163], v[166:167]
	v_lshlrev_b32_e32 v164, 16, v88
	v_and_b32_e32 v165, 0xffff0000, v88
	v_lshlrev_b32_e32 v166, 16, v89
	v_and_b32_e32 v167, 0xffff0000, v89
	v_pk_add_f32 v[160:161], v[160:161], v[164:165]
	v_pk_add_f32 v[162:163], v[162:163], v[166:167]
	v_pk_fma_f32 v[160:161], v[188:189], v[160:161], v[164:165] op_sel_hi:[0,1,1] neg_lo:[0,0,1] neg_hi:[0,0,1]
	v_pk_fma_f32 v[162:163], v[188:189], v[162:163], v[166:167] op_sel_hi:[0,1,1] neg_lo:[0,0,1] neg_hi:[0,0,1]
	v_cvt_pk_bf16_f32 v160, v160, v161
	v_cvt_pk_bf16_f32 v161, v162, v163
	global_store_dwordx2 v64, v[160:161], s[48:49] offset:1024
	s_nop 1
	v_lshlrev_b32_e32 v160, 16, v142
	v_and_b32_e32 v161, 0xffff0000, v142
	v_lshlrev_b32_e32 v162, 16, v143
	v_and_b32_e32 v163, 0xffff0000, v143
	v_pk_add_f32 v[160:161], v[160:161], 0 op_sel_hi:[1,0]
	v_pk_add_f32 v[162:163], v[162:163], 0 op_sel_hi:[1,0]
	v_lshlrev_b32_e32 v164, 16, v140
	v_and_b32_e32 v165, 0xffff0000, v140
	v_lshlrev_b32_e32 v166, 16, v141
	v_and_b32_e32 v167, 0xffff0000, v141
	v_pk_add_f32 v[160:161], v[160:161], v[164:165]
	v_pk_add_f32 v[162:163], v[162:163], v[166:167]
	v_lshlrev_b32_e32 v164, 16, v138
	v_and_b32_e32 v165, 0xffff0000, v138
	v_lshlrev_b32_e32 v166, 16, v139
	v_and_b32_e32 v167, 0xffff0000, v139
	v_pk_add_f32 v[160:161], v[160:161], v[164:165]
	v_pk_add_f32 v[162:163], v[162:163], v[166:167]
	v_lshlrev_b32_e32 v164, 16, v136
	v_and_b32_e32 v165, 0xffff0000, v136
	v_lshlrev_b32_e32 v166, 16, v137
	v_and_b32_e32 v167, 0xffff0000, v137
	v_pk_add_f32 v[160:161], v[160:161], v[164:165]
	v_pk_add_f32 v[162:163], v[162:163], v[166:167]
	v_lshlrev_b32_e32 v164, 16, v134
	v_and_b32_e32 v165, 0xffff0000, v134
	v_lshlrev_b32_e32 v166, 16, v135
	v_and_b32_e32 v167, 0xffff0000, v135
	v_pk_add_f32 v[160:161], v[160:161], v[164:165]
	v_pk_add_f32 v[162:163], v[162:163], v[166:167]
	v_lshlrev_b32_e32 v164, 16, v132
	v_and_b32_e32 v165, 0xffff0000, v132
	v_lshlrev_b32_e32 v166, 16, v133
	v_and_b32_e32 v167, 0xffff0000, v133
	v_pk_add_f32 v[160:161], v[160:161], v[164:165]
	v_pk_add_f32 v[162:163], v[162:163], v[166:167]
	v_lshlrev_b32_e32 v164, 16, v130
	v_and_b32_e32 v165, 0xffff0000, v130
	v_lshlrev_b32_e32 v166, 16, v131
	v_and_b32_e32 v167, 0xffff0000, v131
	v_pk_add_f32 v[160:161], v[160:161], v[164:165]
	v_pk_add_f32 v[162:163], v[162:163], v[166:167]
	v_lshlrev_b32_e32 v164, 16, v128
	v_and_b32_e32 v165, 0xffff0000, v128
	v_lshlrev_b32_e32 v166, 16, v129
	v_and_b32_e32 v167, 0xffff0000, v129
	v_pk_add_f32 v[160:161], v[160:161], v[164:165]
	v_pk_add_f32 v[162:163], v[162:163], v[166:167]
	v_lshlrev_b32_e32 v164, 16, v126
	v_and_b32_e32 v165, 0xffff0000, v126
	v_lshlrev_b32_e32 v166, 16, v127
	v_and_b32_e32 v167, 0xffff0000, v127
	v_pk_add_f32 v[160:161], v[160:161], v[164:165]
	v_pk_add_f32 v[162:163], v[162:163], v[166:167]
	v_lshlrev_b32_e32 v164, 16, v122
	v_and_b32_e32 v165, 0xffff0000, v122
	v_lshlrev_b32_e32 v166, 16, v123
	v_and_b32_e32 v167, 0xffff0000, v123
	v_pk_add_f32 v[160:161], v[160:161], v[164:165]
	v_pk_add_f32 v[162:163], v[162:163], v[166:167]
	v_lshlrev_b32_e32 v164, 16, v118
	v_and_b32_e32 v165, 0xffff0000, v118
	v_lshlrev_b32_e32 v166, 16, v119
	v_and_b32_e32 v167, 0xffff0000, v119
	v_pk_add_f32 v[160:161], v[160:161], v[164:165]
	v_pk_add_f32 v[162:163], v[162:163], v[166:167]
	v_lshlrev_b32_e32 v164, 16, v114
	v_and_b32_e32 v165, 0xffff0000, v114
	v_lshlrev_b32_e32 v166, 16, v115
	v_and_b32_e32 v167, 0xffff0000, v115
	v_pk_add_f32 v[160:161], v[160:161], v[164:165]
	v_pk_add_f32 v[162:163], v[162:163], v[166:167]
	v_lshlrev_b32_e32 v164, 16, v110
	v_and_b32_e32 v165, 0xffff0000, v110
	v_lshlrev_b32_e32 v166, 16, v111
	v_and_b32_e32 v167, 0xffff0000, v111
	v_pk_add_f32 v[160:161], v[160:161], v[164:165]
	v_pk_add_f32 v[162:163], v[162:163], v[166:167]
	v_lshlrev_b32_e32 v164, 16, v104
	v_and_b32_e32 v165, 0xffff0000, v104
	v_lshlrev_b32_e32 v166, 16, v105
	v_and_b32_e32 v167, 0xffff0000, v105
	v_pk_add_f32 v[160:161], v[160:161], v[164:165]
	v_pk_add_f32 v[162:163], v[162:163], v[166:167]
	v_lshlrev_b32_e32 v164, 16, v98
	v_and_b32_e32 v165, 0xffff0000, v98
	v_lshlrev_b32_e32 v166, 16, v99
	v_and_b32_e32 v167, 0xffff0000, v99
	v_pk_add_f32 v[160:161], v[160:161], v[164:165]
	v_pk_add_f32 v[162:163], v[162:163], v[166:167]
	v_lshlrev_b32_e32 v164, 16, v90
	v_and_b32_e32 v165, 0xffff0000, v90
	v_lshlrev_b32_e32 v166, 16, v91
	v_and_b32_e32 v167, 0xffff0000, v91
	v_pk_add_f32 v[160:161], v[160:161], v[164:165]
	v_pk_add_f32 v[162:163], v[162:163], v[166:167]
	v_pk_fma_f32 v[160:161], v[190:191], v[160:161], v[164:165] op_sel_hi:[0,1,1] neg_lo:[0,0,1] neg_hi:[0,0,1]
	v_pk_fma_f32 v[162:163], v[190:191], v[162:163], v[166:167] op_sel_hi:[0,1,1] neg_lo:[0,0,1] neg_hi:[0,0,1]
	v_cvt_pk_bf16_f32 v160, v160, v161
	v_cvt_pk_bf16_f32 v161, v162, v163
	global_store_dwordx2 v64, v[160:161], s[48:49] offset:1536
	s_nop 1
	s_add_u32 s44, s44, s45
	s_cmp_lt_u32 s44, 0x2010
	s_cbranch_scc1 .Lp3f_loop
